# adaLN modulation GEMV hand-written: K split over 16 workgroups with f32 atomic combine; only the first-needed third in the prologue, rest in idle time of layer-0 merge phase
# speedup vs baseline: 1.0558x; 1.0134x over previous
; #define LAS __attribute__((address_space(3)))
; __device__ __forceinline__ float sigmoidf_(float x) { return 1.f / (1.f + __expf(-x)); }
; __device__ __forceinline__ void mod_items(ArgsP a, LAS unsigned char* lds, int bid, int G, int wave, int lane) {
;     LAS float* sil = (LAS float*)lds;
;     LAS float* part = (LAS float*)(lds + 40960);
;     float* MOD = (float*)(a->ws + WS_MOD); const int tid = wave * 64 + lane;
;     for (int e = tid; e < 5 * DM; e += 512) { const int b5 = e >> 11, k = e & 2047; const float cvv = b5 < 4 ? a->in[1][b5 * DM + k] : a->in[3][k]; sil[e] = cvv * sigmoidf_(cvv); }
;     __syncthreads();
;     for (int it = bid; it < 2 * 48; it += G) {
;         const int l = it / 48, cgp = it % 48, n0 = cgp * 256 + lane * 4, k0 = wave * 256;
;         const float* W = a->in[4] + (size_t)l * DM * 12288 + (size_t)k0 * 12288 + n0;
;         f32x4 acc[5];
; #pragma unroll
;         for (int b = 0; b < 5; ++b) acc[b] = (f32x4){0.f, 0.f, 0.f, 0.f};
.LBB0_363:
	s_and_b32 s2, s33, 0xffffffc0
	v_or_b32_e32 v22, s2, v69
	s_movk_i32 s2, 0x2800
	v_cmp_gt_i32_e32 vcc, s2, v22
	s_barrier
	s_load_dwordx2 s[4:5], s[10:11], 0x8
	s_load_dwordx2 s[6:7], s[10:11], 0x18
	v_lshlrev_b32_e32 v2, 2, v22
	s_waitcnt lgkmcnt(0)
	global_load_dword v30, v2, s[4:5]
	s_add_u32 s12, s4, 0x800
	s_addc_u32 s13, s5, 0
	global_load_dword v31, v2, s[12:13]
	s_add_u32 s12, s4, 0x1000
	s_addc_u32 s13, s5, 0
	global_load_dword v32, v2, s[12:13]
	s_add_u32 s12, s4, 0x1800
	s_addc_u32 s13, s5, 0
	global_load_dword v33, v2, s[12:13]
	s_add_u32 s12, s4, 0x2000
	s_addc_u32 s13, s5, 0
	global_load_dword v34, v2, s[12:13]
	s_add_u32 s12, s4, 0x2800
	s_addc_u32 s13, s5, 0
	global_load_dword v35, v2, s[12:13]
	s_add_u32 s12, s4, 0x3000
	s_addc_u32 s13, s5, 0
	global_load_dword v36, v2, s[12:13]
	s_add_u32 s12, s4, 0x3800
	s_addc_u32 s13, s5, 0
	global_load_dword v37, v2, s[12:13]
	s_add_u32 s12, s4, 0x4000
	s_addc_u32 s13, s5, 0
	global_load_dword v38, v2, s[12:13]
	s_add_u32 s12, s4, 0x4800
	s_addc_u32 s13, s5, 0
	global_load_dword v39, v2, s[12:13]
	s_add_u32 s12, s4, 0x5000
	s_addc_u32 s13, s5, 0
	global_load_dword v40, v2, s[12:13]
	s_add_u32 s12, s4, 0x5800
	s_addc_u32 s13, s5, 0
	global_load_dword v41, v2, s[12:13]
	s_add_u32 s12, s4, 0x6000
	s_addc_u32 s13, s5, 0
	global_load_dword v42, v2, s[12:13]
	s_add_u32 s12, s4, 0x6800
	s_addc_u32 s13, s5, 0
	global_load_dword v43, v2, s[12:13]
	s_add_u32 s12, s4, 0x7000
	s_addc_u32 s13, s5, 0
	global_load_dword v44, v2, s[12:13]
	s_add_u32 s12, s4, 0x7800
	s_addc_u32 s13, s5, 0
	global_load_dword v45, v2, s[12:13]
	global_load_dword v46, v2, s[6:7]
	s_add_u32 s12, s6, 0x800
	s_addc_u32 s13, s7, 0
	global_load_dword v47, v2, s[12:13]
	s_add_u32 s12, s6, 0x1000
	s_addc_u32 s13, s7, 0
	global_load_dword v48, v2, s[12:13]
	s_add_u32 s12, s6, 0x1800
	s_addc_u32 s13, s7, 0
	global_load_dword v49, v2, s[12:13]
	s_waitcnt vmcnt(19)
	v_mul_f32_e32 v80, 0xbfb8aa3b, v30
	s_waitcnt vmcnt(18)
	v_mul_f32_e32 v81, 0xbfb8aa3b, v31
	s_waitcnt vmcnt(17)
	v_mul_f32_e32 v82, 0xbfb8aa3b, v32
	s_waitcnt vmcnt(16)
	v_mul_f32_e32 v83, 0xbfb8aa3b, v33
	s_waitcnt vmcnt(15)
	v_mul_f32_e32 v84, 0xbfb8aa3b, v34
	s_waitcnt vmcnt(14)
	v_mul_f32_e32 v85, 0xbfb8aa3b, v35
	s_waitcnt vmcnt(13)
	v_mul_f32_e32 v86, 0xbfb8aa3b, v36
	s_waitcnt vmcnt(12)
	v_mul_f32_e32 v87, 0xbfb8aa3b, v37
	s_waitcnt vmcnt(11)
	v_mul_f32_e32 v88, 0xbfb8aa3b, v38
	s_waitcnt vmcnt(10)
	v_mul_f32_e32 v89, 0xbfb8aa3b, v39
	s_waitcnt vmcnt(9)
	v_mul_f32_e32 v90, 0xbfb8aa3b, v40
	s_waitcnt vmcnt(8)
	v_mul_f32_e32 v91, 0xbfb8aa3b, v41
	s_waitcnt vmcnt(7)
	v_mul_f32_e32 v92, 0xbfb8aa3b, v42
	s_waitcnt vmcnt(6)
	v_mul_f32_e32 v93, 0xbfb8aa3b, v43
	s_waitcnt vmcnt(5)
	v_mul_f32_e32 v94, 0xbfb8aa3b, v44
	s_waitcnt vmcnt(4)
	v_mul_f32_e32 v95, 0xbfb8aa3b, v45
	s_waitcnt vmcnt(3)
	v_mul_f32_e32 v96, 0xbfb8aa3b, v46
	s_waitcnt vmcnt(2)
	v_mul_f32_e32 v97, 0xbfb8aa3b, v47
	s_waitcnt vmcnt(1)
	v_mul_f32_e32 v98, 0xbfb8aa3b, v48
	s_waitcnt vmcnt(0)
	v_mul_f32_e32 v99, 0xbfb8aa3b, v49
	v_exp_f32_e32 v80, v80
	v_exp_f32_e32 v81, v81
	v_exp_f32_e32 v82, v82
	v_exp_f32_e32 v83, v83
	v_exp_f32_e32 v84, v84
	v_exp_f32_e32 v85, v85
	v_exp_f32_e32 v86, v86
	v_exp_f32_e32 v87, v87
	v_exp_f32_e32 v88, v88
	v_exp_f32_e32 v89, v89
	v_exp_f32_e32 v90, v90
	v_exp_f32_e32 v91, v91
	v_exp_f32_e32 v92, v92
	v_exp_f32_e32 v93, v93
	v_exp_f32_e32 v94, v94
	v_exp_f32_e32 v95, v95
	v_exp_f32_e32 v96, v96
	v_exp_f32_e32 v97, v97
	v_exp_f32_e32 v98, v98
	v_exp_f32_e32 v99, v99
	v_add_f32_e32 v80, 1.0, v80
	v_add_f32_e32 v81, 1.0, v81
	v_add_f32_e32 v82, 1.0, v82
	v_add_f32_e32 v83, 1.0, v83
	v_add_f32_e32 v84, 1.0, v84
	v_add_f32_e32 v85, 1.0, v85
	v_add_f32_e32 v86, 1.0, v86
	v_add_f32_e32 v87, 1.0, v87
	v_add_f32_e32 v88, 1.0, v88
	v_add_f32_e32 v89, 1.0, v89
	v_add_f32_e32 v90, 1.0, v90
	v_add_f32_e32 v91, 1.0, v91
	v_add_f32_e32 v92, 1.0, v92
	v_add_f32_e32 v93, 1.0, v93
	v_add_f32_e32 v94, 1.0, v94
	v_add_f32_e32 v95, 1.0, v95
	v_add_f32_e32 v96, 1.0, v96
	v_add_f32_e32 v97, 1.0, v97
	v_add_f32_e32 v98, 1.0, v98
	v_add_f32_e32 v99, 1.0, v99
	v_rcp_f32_e32 v80, v80
	v_rcp_f32_e32 v81, v81
	v_rcp_f32_e32 v82, v82
	v_rcp_f32_e32 v83, v83
	v_rcp_f32_e32 v84, v84
	v_rcp_f32_e32 v85, v85
	v_rcp_f32_e32 v86, v86
	v_rcp_f32_e32 v87, v87
	v_rcp_f32_e32 v88, v88
	v_rcp_f32_e32 v89, v89
	v_rcp_f32_e32 v90, v90
	v_rcp_f32_e32 v91, v91
	v_rcp_f32_e32 v92, v92
	v_rcp_f32_e32 v93, v93
	v_rcp_f32_e32 v94, v94
	v_rcp_f32_e32 v95, v95
	v_rcp_f32_e32 v96, v96
	v_rcp_f32_e32 v97, v97
	v_rcp_f32_e32 v98, v98
	v_rcp_f32_e32 v99, v99
	v_mul_f32_e32 v30, v30, v80
	v_mul_f32_e32 v31, v31, v81
	v_mul_f32_e32 v32, v32, v82
	v_mul_f32_e32 v33, v33, v83
	v_mul_f32_e32 v34, v34, v84
	v_mul_f32_e32 v35, v35, v85
	v_mul_f32_e32 v36, v36, v86
	v_mul_f32_e32 v37, v37, v87
	v_mul_f32_e32 v38, v38, v88
	v_mul_f32_e32 v39, v39, v89
	v_mul_f32_e32 v40, v40, v90
	v_mul_f32_e32 v41, v41, v91
	v_mul_f32_e32 v42, v42, v92
	v_mul_f32_e32 v43, v43, v93
	v_mul_f32_e32 v44, v44, v94
	v_mul_f32_e32 v45, v45, v95
	v_mul_f32_e32 v46, v46, v96
	v_mul_f32_e32 v47, v47, v97
	v_mul_f32_e32 v48, v48, v98
	v_mul_f32_e32 v49, v49, v99
	ds_write_b32 v2, v30
	ds_write_b32 v2, v31 offset:2048
	ds_write_b32 v2, v32 offset:4096
	ds_write_b32 v2, v33 offset:6144
	ds_write_b32 v2, v34 offset:8192
	ds_write_b32 v2, v35 offset:10240
	ds_write_b32 v2, v36 offset:12288
	ds_write_b32 v2, v37 offset:14336
	ds_write_b32 v2, v38 offset:16384
	ds_write_b32 v2, v39 offset:18432
	ds_write_b32 v2, v40 offset:20480
	ds_write_b32 v2, v41 offset:22528
	ds_write_b32 v2, v42 offset:24576
	ds_write_b32 v2, v43 offset:26624
	ds_write_b32 v2, v44 offset:28672
	ds_write_b32 v2, v45 offset:30720
	ds_write_b32 v2, v46 offset:32768
	ds_write_b32 v2, v47 offset:34816
	ds_write_b32 v2, v48 offset:36864
	ds_write_b32 v2, v49 offset:38912
	v_and_b32_e32 v23, 63, v206
	v_lshrrev_b32_e32 v24, 6, v206
	s_load_dwordx2 s[14:15], s[0:1], 0x20
	s_load_dwordx2 s[18:19], s[0:1], 0x28
	s_load_dwordx2 s[20:21], s[0:1], 0xd0
	v_readfirstlane_b32 s2, v24
	v_lshlrev_b32_e32 v25, 4, v23
	s_waitcnt lgkmcnt(0)
	s_waitcnt lgkmcnt(0)
	s_barrier
	s_lshl_b32 s4, s2, 4
	s_mul_i32 s5, s2, 0x1400
	v_add_u32_e32 v27, s5, v25
	v_add_u32_e32 v27, 0xa000, v27
	v_lshlrev_b32_e32 v28, 2, v206
	v_add_u32_e32 v28, 0xa000, v28
	v_lshrrev_b32_e32 v29, 8, v206
	v_and_b32_e32 v30, 0xff, v206
	v_mul_u32_u24_e32 v29, 0x3000, v29
	v_add_u32_e32 v29, v29, v30
	v_lshlrev_b32_e32 v29, 2, v29
	v_lshlrev_b32_e32 v30, 2, v30
	s_add_u32 s20, s20, 0x100000
	s_addc_u32 s21, s21, 0
	s_mov_b32 s3, s8
	s_cmp_ge_u32 s3, 256
	s_cbranch_scc1 .Lmy_mdp_done
; __device__ __forceinline__ void mod_items(ArgsP a, LAS unsigned char* lds, int bid, int G, int wave, int lane) {
;     ...
;     for (int it = bid; it < 2 * 48; it += G) {
;         const int l = it / 48, cgp = it % 48, n0 = cgp * 256 + lane * 4, k0 = wave * 256;
;         const float* W = a->in[4] + (size_t)l * DM * 12288 + (size_t)k0 * 12288 + n0;
;         f32x4 acc[5];
; #pragma unroll
;         for (int b = 0; b < 5; ++b) acc[b] = (f32x4){0.f, 0.f, 0.f, 0.f};
; #pragma unroll 8
;         for (int kk = 0; kk < 256; ++kk) { const f32x4 w = __builtin_nontemporal_load((const f32x4*)(W + (size_t)kk * 12288));
; #pragma unroll
;             for (int b = 0; b < 5; ++b) acc[b] += w * sil[b * DM + k0 + kk]; }
.Lmy_mdp_loop:
	s_lshr_b32 s35, s3, 4
	s_and_b32 s40, s3, 15
	s_cmp_ge_u32 s35, 48
	s_cselect_b32 s42, 1, 0
	s_mul_i32 s43, s42, 48
	s_sub_i32 s43, s35, s43
	s_lshl_b32 s48, s40, 7
	s_add_i32 s48, s48, s4
	s_lshl_b32 s51, s42, 11
	s_add_i32 s51, s51, s48
	s_mul_hi_u32 s55, s51, 0xc000
	s_mul_i32 s54, s51, 0xc000
	s_lshl_b32 s57, s43, 10
	s_add_u32 s54, s54, s57
	s_addc_u32 s55, s55, 0
	s_add_u32 s26, s14, s54
	s_addc_u32 s27, s15, s55
	s_lshl_b32 s57, s48, 2
	v_mov_b32_e32 v31, s57
	v_mov_b32_e32 v2, 0
	v_mov_b32_e32 v3, 0
	v_mov_b32_e32 v4, 0
	v_mov_b32_e32 v5, 0
	v_mov_b32_e32 v6, 0
	v_mov_b32_e32 v7, 0
	v_mov_b32_e32 v8, 0
	v_mov_b32_e32 v9, 0
	v_mov_b32_e32 v10, 0
	v_mov_b32_e32 v11, 0
	v_mov_b32_e32 v12, 0
	v_mov_b32_e32 v13, 0
	v_mov_b32_e32 v14, 0
	v_mov_b32_e32 v15, 0
	v_mov_b32_e32 v16, 0
	v_mov_b32_e32 v17, 0
	v_mov_b32_e32 v18, 0
	v_mov_b32_e32 v19, 0
	v_mov_b32_e32 v20, 0
	v_mov_b32_e32 v21, 0
	global_load_dwordx4 v[32:35], v25, s[26:27] nt
	s_add_u32 s26, s26, 0xc000
	s_addc_u32 s27, s27, 0
	global_load_dwordx4 v[36:39], v25, s[26:27] nt
	s_add_u32 s26, s26, 0xc000
	s_addc_u32 s27, s27, 0
	global_load_dwordx4 v[40:43], v25, s[26:27] nt
	s_add_u32 s26, s26, 0xc000
	s_addc_u32 s27, s27, 0
	global_load_dwordx4 v[44:47], v25, s[26:27] nt
	s_add_u32 s26, s26, 0xc000
	s_addc_u32 s27, s27, 0
	global_load_dwordx4 v[48:51], v25, s[26:27] nt
	s_add_u32 s26, s26, 0xc000
	s_addc_u32 s27, s27, 0
	global_load_dwordx4 v[52:55], v25, s[26:27] nt
	s_add_u32 s26, s26, 0xc000
	s_addc_u32 s27, s27, 0
	global_load_dwordx4 v[56:59], v25, s[26:27] nt
	s_add_u32 s26, s26, 0xc000
	s_addc_u32 s27, s27, 0
	global_load_dwordx4 v[60:63], v25, s[26:27] nt
	s_add_u32 s26, s26, 0xc000
	s_addc_u32 s27, s27, 0
	ds_read_b128 v[164:167], v31 offset:0
	ds_read_b128 v[168:171], v31 offset:8192
	ds_read_b128 v[172:175], v31 offset:16384
	ds_read_b128 v[176:179], v31 offset:24576
	ds_read_b128 v[180:183], v31 offset:32768
	s_waitcnt lgkmcnt(0)
	s_waitcnt vmcnt(7)
	v_fmac_f32_e32 v2, v32, v164
	v_fmac_f32_e32 v3, v33, v164
	v_fmac_f32_e32 v4, v34, v164
	v_fmac_f32_e32 v5, v35, v164
	v_fmac_f32_e32 v6, v32, v168
	v_fmac_f32_e32 v7, v33, v168
	v_fmac_f32_e32 v8, v34, v168
	v_fmac_f32_e32 v9, v35, v168
	v_fmac_f32_e32 v10, v32, v172
	v_fmac_f32_e32 v11, v33, v172
	v_fmac_f32_e32 v12, v34, v172
	v_fmac_f32_e32 v13, v35, v172
	v_fmac_f32_e32 v14, v32, v176
	v_fmac_f32_e32 v15, v33, v176
	v_fmac_f32_e32 v16, v34, v176
	v_fmac_f32_e32 v17, v35, v176
	v_fmac_f32_e32 v18, v32, v180
	v_fmac_f32_e32 v19, v33, v180
	v_fmac_f32_e32 v20, v34, v180
	v_fmac_f32_e32 v21, v35, v180
	global_load_dwordx4 v[32:35], v25, s[26:27] nt
	s_add_u32 s26, s26, 0xc000
	s_addc_u32 s27, s27, 0
	s_waitcnt vmcnt(7)
	v_fmac_f32_e32 v2, v36, v165
	v_fmac_f32_e32 v3, v37, v165
	v_fmac_f32_e32 v4, v38, v165
	v_fmac_f32_e32 v5, v39, v165
	v_fmac_f32_e32 v6, v36, v169
	v_fmac_f32_e32 v7, v37, v169
	v_fmac_f32_e32 v8, v38, v169
	v_fmac_f32_e32 v9, v39, v169
	v_fmac_f32_e32 v10, v36, v173
	v_fmac_f32_e32 v11, v37, v173
	v_fmac_f32_e32 v12, v38, v173
	v_fmac_f32_e32 v13, v39, v173
	v_fmac_f32_e32 v14, v36, v177
	v_fmac_f32_e32 v15, v37, v177
	v_fmac_f32_e32 v16, v38, v177
	v_fmac_f32_e32 v17, v39, v177
	v_fmac_f32_e32 v18, v36, v181
	v_fmac_f32_e32 v19, v37, v181
	v_fmac_f32_e32 v20, v38, v181
	v_fmac_f32_e32 v21, v39, v181
	global_load_dwordx4 v[36:39], v25, s[26:27] nt
	s_add_u32 s26, s26, 0xc000
	s_addc_u32 s27, s27, 0
	s_waitcnt vmcnt(7)
	v_fmac_f32_e32 v2, v40, v166
	v_fmac_f32_e32 v3, v41, v166
	v_fmac_f32_e32 v4, v42, v166
	v_fmac_f32_e32 v5, v43, v166
	v_fmac_f32_e32 v6, v40, v170
	v_fmac_f32_e32 v7, v41, v170
	v_fmac_f32_e32 v8, v42, v170
	v_fmac_f32_e32 v9, v43, v170
	v_fmac_f32_e32 v10, v40, v174
	v_fmac_f32_e32 v11, v41, v174
	v_fmac_f32_e32 v12, v42, v174
	v_fmac_f32_e32 v13, v43, v174
	v_fmac_f32_e32 v14, v40, v178
	v_fmac_f32_e32 v15, v41, v178
	v_fmac_f32_e32 v16, v42, v178
	v_fmac_f32_e32 v17, v43, v178
	v_fmac_f32_e32 v18, v40, v182
	v_fmac_f32_e32 v19, v41, v182
	v_fmac_f32_e32 v20, v42, v182
	v_fmac_f32_e32 v21, v43, v182
	global_load_dwordx4 v[40:43], v25, s[26:27] nt
	s_add_u32 s26, s26, 0xc000
	s_addc_u32 s27, s27, 0
	s_waitcnt vmcnt(7)
	v_fmac_f32_e32 v2, v44, v167
	v_fmac_f32_e32 v3, v45, v167
	v_fmac_f32_e32 v4, v46, v167
	v_fmac_f32_e32 v5, v47, v167
	v_fmac_f32_e32 v6, v44, v171
	v_fmac_f32_e32 v7, v45, v171
	v_fmac_f32_e32 v8, v46, v171
	v_fmac_f32_e32 v9, v47, v171
	v_fmac_f32_e32 v10, v44, v175
	v_fmac_f32_e32 v11, v45, v175
	v_fmac_f32_e32 v12, v46, v175
	v_fmac_f32_e32 v13, v47, v175
	v_fmac_f32_e32 v14, v44, v179
	v_fmac_f32_e32 v15, v45, v179
	v_fmac_f32_e32 v16, v46, v179
	v_fmac_f32_e32 v17, v47, v179
	v_fmac_f32_e32 v18, v44, v183
	v_fmac_f32_e32 v19, v45, v183
	v_fmac_f32_e32 v20, v46, v183
	v_fmac_f32_e32 v21, v47, v183
	global_load_dwordx4 v[44:47], v25, s[26:27] nt
	s_add_u32 s26, s26, 0xc000
	s_addc_u32 s27, s27, 0
	ds_read_b128 v[164:167], v31 offset:16
	ds_read_b128 v[168:171], v31 offset:8208
	ds_read_b128 v[172:175], v31 offset:16400
	ds_read_b128 v[176:179], v31 offset:24592
	ds_read_b128 v[180:183], v31 offset:32784
	s_waitcnt lgkmcnt(0)
	s_waitcnt vmcnt(7)
	v_fmac_f32_e32 v2, v48, v164
	v_fmac_f32_e32 v3, v49, v164
	v_fmac_f32_e32 v4, v50, v164
	v_fmac_f32_e32 v5, v51, v164
	v_fmac_f32_e32 v6, v48, v168
	v_fmac_f32_e32 v7, v49, v168
	v_fmac_f32_e32 v8, v50, v168
	v_fmac_f32_e32 v9, v51, v168
	v_fmac_f32_e32 v10, v48, v172
	v_fmac_f32_e32 v11, v49, v172
	v_fmac_f32_e32 v12, v50, v172
	v_fmac_f32_e32 v13, v51, v172
	v_fmac_f32_e32 v14, v48, v176
	v_fmac_f32_e32 v15, v49, v176
	v_fmac_f32_e32 v16, v50, v176
	v_fmac_f32_e32 v17, v51, v176
	v_fmac_f32_e32 v18, v48, v180
	v_fmac_f32_e32 v19, v49, v180
	v_fmac_f32_e32 v20, v50, v180
	v_fmac_f32_e32 v21, v51, v180
	global_load_dwordx4 v[48:51], v25, s[26:27] nt
	s_add_u32 s26, s26, 0xc000
	s_addc_u32 s27, s27, 0
	s_waitcnt vmcnt(7)
; __device__ __forceinline__ void mod_items(ArgsP a, LAS unsigned char* lds, int bid, int G, int wave, int lane) {
;     ...
; #pragma unroll 8
;         for (int kk = 0; kk < 256; ++kk) { const f32x4 w = __builtin_nontemporal_load((const f32x4*)(W + (size_t)kk * 12288));
; #pragma unroll
;             for (int b = 0; b < 5; ++b) acc[b] += w * sil[b * DM + k0 + kk]; }
	v_fmac_f32_e32 v2, v52, v165
	v_fmac_f32_e32 v3, v53, v165
	v_fmac_f32_e32 v4, v54, v165
	v_fmac_f32_e32 v5, v55, v165
	v_fmac_f32_e32 v6, v52, v169
	v_fmac_f32_e32 v7, v53, v169
	v_fmac_f32_e32 v8, v54, v169
	v_fmac_f32_e32 v9, v55, v169
	v_fmac_f32_e32 v10, v52, v173
	v_fmac_f32_e32 v11, v53, v173
	v_fmac_f32_e32 v12, v54, v173
	v_fmac_f32_e32 v13, v55, v173
	v_fmac_f32_e32 v14, v52, v177
	v_fmac_f32_e32 v15, v53, v177
	v_fmac_f32_e32 v16, v54, v177
	v_fmac_f32_e32 v17, v55, v177
	v_fmac_f32_e32 v18, v52, v181
	v_fmac_f32_e32 v19, v53, v181
	v_fmac_f32_e32 v20, v54, v181
	v_fmac_f32_e32 v21, v55, v181
	global_load_dwordx4 v[52:55], v25, s[26:27] nt
	s_add_u32 s26, s26, 0xc000
	s_addc_u32 s27, s27, 0
	s_waitcnt vmcnt(7)
	v_fmac_f32_e32 v2, v56, v166
	v_fmac_f32_e32 v3, v57, v166
	v_fmac_f32_e32 v4, v58, v166
	v_fmac_f32_e32 v5, v59, v166
	v_fmac_f32_e32 v6, v56, v170
	v_fmac_f32_e32 v7, v57, v170
	v_fmac_f32_e32 v8, v58, v170
	v_fmac_f32_e32 v9, v59, v170
	v_fmac_f32_e32 v10, v56, v174
	v_fmac_f32_e32 v11, v57, v174
	v_fmac_f32_e32 v12, v58, v174
	v_fmac_f32_e32 v13, v59, v174
	v_fmac_f32_e32 v14, v56, v178
	v_fmac_f32_e32 v15, v57, v178
	v_fmac_f32_e32 v16, v58, v178
	v_fmac_f32_e32 v17, v59, v178
	v_fmac_f32_e32 v18, v56, v182
	v_fmac_f32_e32 v19, v57, v182
	v_fmac_f32_e32 v20, v58, v182
	v_fmac_f32_e32 v21, v59, v182
	global_load_dwordx4 v[56:59], v25, s[26:27] nt
	s_add_u32 s26, s26, 0xc000
	s_addc_u32 s27, s27, 0
	s_waitcnt vmcnt(7)
	v_fmac_f32_e32 v2, v60, v167
	v_fmac_f32_e32 v3, v61, v167
	v_fmac_f32_e32 v4, v62, v167
	v_fmac_f32_e32 v5, v63, v167
	v_fmac_f32_e32 v6, v60, v171
	v_fmac_f32_e32 v7, v61, v171
	v_fmac_f32_e32 v8, v62, v171
	v_fmac_f32_e32 v9, v63, v171
	v_fmac_f32_e32 v10, v60, v175
	v_fmac_f32_e32 v11, v61, v175
	v_fmac_f32_e32 v12, v62, v175
	v_fmac_f32_e32 v13, v63, v175
	v_fmac_f32_e32 v14, v60, v179
	v_fmac_f32_e32 v15, v61, v179
	v_fmac_f32_e32 v16, v62, v179
	v_fmac_f32_e32 v17, v63, v179
	v_fmac_f32_e32 v18, v60, v183
	v_fmac_f32_e32 v19, v61, v183
	v_fmac_f32_e32 v20, v62, v183
	v_fmac_f32_e32 v21, v63, v183
	global_load_dwordx4 v[60:63], v25, s[26:27] nt
	ds_read_b128 v[164:167], v31 offset:32
	ds_read_b128 v[168:171], v31 offset:8224
	ds_read_b128 v[172:175], v31 offset:16416
	ds_read_b128 v[176:179], v31 offset:24608
	ds_read_b128 v[180:183], v31 offset:32800
	s_waitcnt lgkmcnt(0)
	s_waitcnt vmcnt(7)
	v_fmac_f32_e32 v2, v32, v164
	v_fmac_f32_e32 v3, v33, v164
	v_fmac_f32_e32 v4, v34, v164
	v_fmac_f32_e32 v5, v35, v164
	v_fmac_f32_e32 v6, v32, v168
	v_fmac_f32_e32 v7, v33, v168
	v_fmac_f32_e32 v8, v34, v168
	v_fmac_f32_e32 v9, v35, v168
	v_fmac_f32_e32 v10, v32, v172
	v_fmac_f32_e32 v11, v33, v172
	v_fmac_f32_e32 v12, v34, v172
	v_fmac_f32_e32 v13, v35, v172
	v_fmac_f32_e32 v14, v32, v176
	v_fmac_f32_e32 v15, v33, v176
	v_fmac_f32_e32 v16, v34, v176
	v_fmac_f32_e32 v17, v35, v176
	v_fmac_f32_e32 v18, v32, v180
	v_fmac_f32_e32 v19, v33, v180
	v_fmac_f32_e32 v20, v34, v180
	v_fmac_f32_e32 v21, v35, v180
	s_waitcnt vmcnt(6)
	v_fmac_f32_e32 v2, v36, v165
	v_fmac_f32_e32 v3, v37, v165
	v_fmac_f32_e32 v4, v38, v165
	v_fmac_f32_e32 v5, v39, v165
	v_fmac_f32_e32 v6, v36, v169
	v_fmac_f32_e32 v7, v37, v169
	v_fmac_f32_e32 v8, v38, v169
	v_fmac_f32_e32 v9, v39, v169
	v_fmac_f32_e32 v10, v36, v173
	v_fmac_f32_e32 v11, v37, v173
	v_fmac_f32_e32 v12, v38, v173
	v_fmac_f32_e32 v13, v39, v173
	v_fmac_f32_e32 v14, v36, v177
	v_fmac_f32_e32 v15, v37, v177
	v_fmac_f32_e32 v16, v38, v177
	v_fmac_f32_e32 v17, v39, v177
	v_fmac_f32_e32 v18, v36, v181
	v_fmac_f32_e32 v19, v37, v181
	v_fmac_f32_e32 v20, v38, v181
	v_fmac_f32_e32 v21, v39, v181
	s_waitcnt vmcnt(5)
	v_fmac_f32_e32 v2, v40, v166
	v_fmac_f32_e32 v3, v41, v166
	v_fmac_f32_e32 v4, v42, v166
	v_fmac_f32_e32 v5, v43, v166
	v_fmac_f32_e32 v6, v40, v170
	v_fmac_f32_e32 v7, v41, v170
	v_fmac_f32_e32 v8, v42, v170
	v_fmac_f32_e32 v9, v43, v170
	v_fmac_f32_e32 v10, v40, v174
	v_fmac_f32_e32 v11, v41, v174
	v_fmac_f32_e32 v12, v42, v174
	v_fmac_f32_e32 v13, v43, v174
	v_fmac_f32_e32 v14, v40, v178
	v_fmac_f32_e32 v15, v41, v178
	v_fmac_f32_e32 v16, v42, v178
	v_fmac_f32_e32 v17, v43, v178
	v_fmac_f32_e32 v18, v40, v182
	v_fmac_f32_e32 v19, v41, v182
	v_fmac_f32_e32 v20, v42, v182
	v_fmac_f32_e32 v21, v43, v182
	s_waitcnt vmcnt(4)
	v_fmac_f32_e32 v2, v44, v167
	v_fmac_f32_e32 v3, v45, v167
	v_fmac_f32_e32 v4, v46, v167
	v_fmac_f32_e32 v5, v47, v167
	v_fmac_f32_e32 v6, v44, v171
	v_fmac_f32_e32 v7, v45, v171
	v_fmac_f32_e32 v8, v46, v171
	v_fmac_f32_e32 v9, v47, v171
	v_fmac_f32_e32 v10, v44, v175
	v_fmac_f32_e32 v11, v45, v175
	v_fmac_f32_e32 v12, v46, v175
	v_fmac_f32_e32 v13, v47, v175
	v_fmac_f32_e32 v14, v44, v179
	v_fmac_f32_e32 v15, v45, v179
	v_fmac_f32_e32 v16, v46, v179
	v_fmac_f32_e32 v17, v47, v179
	v_fmac_f32_e32 v18, v44, v183
	v_fmac_f32_e32 v19, v45, v183
	v_fmac_f32_e32 v20, v46, v183
	v_fmac_f32_e32 v21, v47, v183
	ds_read_b128 v[164:167], v31 offset:48
	ds_read_b128 v[168:171], v31 offset:8240
	ds_read_b128 v[172:175], v31 offset:16432
	ds_read_b128 v[176:179], v31 offset:24624
	ds_read_b128 v[180:183], v31 offset:32816
	s_waitcnt lgkmcnt(0)
	s_waitcnt vmcnt(3)
	v_fmac_f32_e32 v2, v48, v164
	v_fmac_f32_e32 v3, v49, v164
	v_fmac_f32_e32 v4, v50, v164
	v_fmac_f32_e32 v5, v51, v164
	v_fmac_f32_e32 v6, v48, v168
	v_fmac_f32_e32 v7, v49, v168
	v_fmac_f32_e32 v8, v50, v168
	v_fmac_f32_e32 v9, v51, v168
	v_fmac_f32_e32 v10, v48, v172
	v_fmac_f32_e32 v11, v49, v172
	v_fmac_f32_e32 v12, v50, v172
	v_fmac_f32_e32 v13, v51, v172
	v_fmac_f32_e32 v14, v48, v176
	v_fmac_f32_e32 v15, v49, v176
	v_fmac_f32_e32 v16, v50, v176
	v_fmac_f32_e32 v17, v51, v176
	v_fmac_f32_e32 v18, v48, v180
	v_fmac_f32_e32 v19, v49, v180
	v_fmac_f32_e32 v20, v50, v180
	v_fmac_f32_e32 v21, v51, v180
	s_waitcnt vmcnt(2)
; #define LAS __attribute__((address_space(3)))
; __device__ __forceinline__ void mod_items(ArgsP a, LAS unsigned char* lds, int bid, int G, int wave, int lane) {
;     ...
;         for (int kk = 0; kk < 256; ++kk) { const f32x4 w = __builtin_nontemporal_load((const f32x4*)(W + (size_t)kk * 12288));
; #pragma unroll
;             for (int b = 0; b < 5; ++b) acc[b] += w * sil[b * DM + k0 + kk]; }
; #pragma unroll
;         for (int b = 0; b < 5; ++b) *(LAS f32x4*)(part + (wave * 5 + b) * 256 + lane * 4) = acc[b];
;         __syncthreads();
;         for (int e = tid; e < 5 * 256; e += 512) { const int b = e >> 8, cidx = e & 255; float sacc = a->in[5][l * 12288 + cgp * 256 + cidx];
; #pragma unroll
;             for (int w8 = 0; w8 < 8; ++w8) sacc += part[(w8 * 5 + b) * 256 + cidx];
;             MOD[(size_t)(l * 5 + b) * 12288 + cgp * 256 + cidx] = sacc; }
;         __syncthreads();
	v_fmac_f32_e32 v2, v52, v165
	v_fmac_f32_e32 v3, v53, v165
	v_fmac_f32_e32 v4, v54, v165
	v_fmac_f32_e32 v5, v55, v165
	v_fmac_f32_e32 v6, v52, v169
	v_fmac_f32_e32 v7, v53, v169
	v_fmac_f32_e32 v8, v54, v169
	v_fmac_f32_e32 v9, v55, v169
	v_fmac_f32_e32 v10, v52, v173
	v_fmac_f32_e32 v11, v53, v173
	v_fmac_f32_e32 v12, v54, v173
	v_fmac_f32_e32 v13, v55, v173
	v_fmac_f32_e32 v14, v52, v177
	v_fmac_f32_e32 v15, v53, v177
	v_fmac_f32_e32 v16, v54, v177
	v_fmac_f32_e32 v17, v55, v177
	v_fmac_f32_e32 v18, v52, v181
	v_fmac_f32_e32 v19, v53, v181
	v_fmac_f32_e32 v20, v54, v181
	v_fmac_f32_e32 v21, v55, v181
	s_waitcnt vmcnt(1)
	v_fmac_f32_e32 v2, v56, v166
	v_fmac_f32_e32 v3, v57, v166
	v_fmac_f32_e32 v4, v58, v166
	v_fmac_f32_e32 v5, v59, v166
	v_fmac_f32_e32 v6, v56, v170
	v_fmac_f32_e32 v7, v57, v170
	v_fmac_f32_e32 v8, v58, v170
	v_fmac_f32_e32 v9, v59, v170
	v_fmac_f32_e32 v10, v56, v174
	v_fmac_f32_e32 v11, v57, v174
	v_fmac_f32_e32 v12, v58, v174
	v_fmac_f32_e32 v13, v59, v174
	v_fmac_f32_e32 v14, v56, v178
	v_fmac_f32_e32 v15, v57, v178
	v_fmac_f32_e32 v16, v58, v178
	v_fmac_f32_e32 v17, v59, v178
	v_fmac_f32_e32 v18, v56, v182
	v_fmac_f32_e32 v19, v57, v182
	v_fmac_f32_e32 v20, v58, v182
	v_fmac_f32_e32 v21, v59, v182
	s_waitcnt vmcnt(0)
	v_fmac_f32_e32 v2, v60, v167
	v_fmac_f32_e32 v3, v61, v167
	v_fmac_f32_e32 v4, v62, v167
	v_fmac_f32_e32 v5, v63, v167
	v_fmac_f32_e32 v6, v60, v171
	v_fmac_f32_e32 v7, v61, v171
	v_fmac_f32_e32 v8, v62, v171
	v_fmac_f32_e32 v9, v63, v171
	v_fmac_f32_e32 v10, v60, v175
	v_fmac_f32_e32 v11, v61, v175
	v_fmac_f32_e32 v12, v62, v175
	v_fmac_f32_e32 v13, v63, v175
	v_fmac_f32_e32 v14, v60, v179
	v_fmac_f32_e32 v15, v61, v179
	v_fmac_f32_e32 v16, v62, v179
	v_fmac_f32_e32 v17, v63, v179
	v_fmac_f32_e32 v18, v60, v183
	v_fmac_f32_e32 v19, v61, v183
	v_fmac_f32_e32 v20, v62, v183
	v_fmac_f32_e32 v21, v63, v183
	ds_write_b128 v27, v[2:5]
	ds_write_b128 v27, v[6:9] offset:1024
	ds_write_b128 v27, v[10:13] offset:2048
	ds_write_b128 v27, v[14:17] offset:3072
	ds_write_b128 v27, v[18:21] offset:4096
	s_waitcnt lgkmcnt(0)
	s_barrier
	s_mul_i32 s57, s42, 0xf000
	s_lshl_b32 s58, s43, 8
	s_add_i32 s57, s57, s58
	s_lshl_b32 s57, s57, 2
	s_add_u32 s68, s20, s57
	s_addc_u32 s69, s21, 0
	s_mul_i32 s57, s42, 0x3000
	s_add_i32 s57, s57, s58
	s_lshl_b32 s57, s57, 2
	s_add_u32 s70, s18, s57
	s_addc_u32 s71, s19, 0
	ds_read_b32 v64, v28 offset:0
	ds_read_b32 v65, v28 offset:5120
	ds_read_b32 v66, v28 offset:10240
	ds_read_b32 v67, v28 offset:15360
	ds_read_b32 v68, v28 offset:20480
	ds_read_b32 v70, v28 offset:25600
	ds_read_b32 v71, v28 offset:30720
	ds_read_b32 v72, v28 offset:35840
	v_mov_b32_e32 v73, 0
	s_cmp_lg_u32 s40, 0
	s_cbranch_scc1 .Lmy_mdp_nb0
	global_load_dword v73, v30, s[70:71]
.Lmy_mdp_nb0:
	s_waitcnt lgkmcnt(0)
	v_add_f32_e32 v64, v64, v65
	v_add_f32_e32 v66, v66, v67
	v_add_f32_e32 v68, v68, v70
	v_add_f32_e32 v71, v71, v72
	v_add_f32_e32 v64, v64, v66
	v_add_f32_e32 v68, v68, v71
	v_add_f32_e32 v64, v64, v68
	s_waitcnt vmcnt(0)
	v_add_f32_e32 v64, v64, v73
	global_atomic_add_f32 v29, v64, s[68:69]
	ds_read_b32 v64, v28 offset:2048
	ds_read_b32 v65, v28 offset:7168
	ds_read_b32 v66, v28 offset:12288
	ds_read_b32 v67, v28 offset:17408
	ds_read_b32 v68, v28 offset:22528
	ds_read_b32 v70, v28 offset:27648
	ds_read_b32 v71, v28 offset:32768
	ds_read_b32 v72, v28 offset:37888
	v_mov_b32_e32 v73, 0
	s_cmp_lg_u32 s40, 0
	s_cbranch_scc1 .Lmy_mdp_nb1
	global_load_dword v73, v30, s[70:71]
.Lmy_mdp_nb1:
	s_waitcnt lgkmcnt(0)
	v_add_f32_e32 v64, v64, v65
	v_add_f32_e32 v66, v66, v67
	v_add_f32_e32 v68, v68, v70
	v_add_f32_e32 v71, v71, v72
	v_add_f32_e32 v64, v64, v66
	v_add_f32_e32 v68, v68, v71
	v_add_f32_e32 v64, v64, v68
	s_waitcnt vmcnt(0)
	v_add_f32_e32 v64, v64, v73
	s_add_u32 s68, s68, 0x18000
	s_addc_u32 s69, s69, 0
	global_atomic_add_f32 v29, v64, s[68:69]
	v_cmp_gt_u32_e32 vcc, 0x100, v206
	s_and_saveexec_b64 s[58:59], vcc
	ds_read_b32 v64, v28 offset:4096
	ds_read_b32 v65, v28 offset:9216
	ds_read_b32 v66, v28 offset:14336
	ds_read_b32 v67, v28 offset:19456
	ds_read_b32 v68, v28 offset:24576
	ds_read_b32 v70, v28 offset:29696
	ds_read_b32 v71, v28 offset:34816
	ds_read_b32 v72, v28 offset:39936
	v_mov_b32_e32 v73, 0
	s_cmp_lg_u32 s40, 0
	s_cbranch_scc1 .Lmy_mdp_nb2
	global_load_dword v73, v30, s[70:71]
.Lmy_mdp_nb2:
	s_waitcnt lgkmcnt(0)
	v_add_f32_e32 v64, v64, v65
	v_add_f32_e32 v66, v66, v67
	v_add_f32_e32 v68, v68, v70
	v_add_f32_e32 v71, v71, v72
	v_add_f32_e32 v64, v64, v66
	v_add_f32_e32 v68, v68, v71
	v_add_f32_e32 v64, v64, v68
	s_waitcnt vmcnt(0)
	v_add_f32_e32 v64, v64, v73
	s_add_u32 s68, s68, 0x18000
	s_addc_u32 s69, s69, 0
	global_atomic_add_f32 v29, v64, s[68:69]
	s_or_b64 exec, exec, s[58:59]
	s_barrier
	s_add_i32 s3, s3, 256
	s_cmp_lt_u32 s3, 256
	s_cbranch_scc1 .Lmy_mdp_loop
; __device__ __forceinline__ void ph_prologue(LAS unsigned char* lds) { PH_PRE
;     ...
;     float* ROPE = (float*)(ws + WS_ROPE);
;     for (int e = bid * 512 + tid; e < 2048 * 32; e += G * 512) { const int t = e >> 5, i = e & 31; const float fr_ = powf(10000.f, -(float)(i & 15) / 16.f); const float pos = (float)(i < 16 ? (t >> 6) : (t & 63));
;         float sn, cs; sincosf(pos * fr_, &sn, &cs); ROPE[e * 2] = cs; ROPE[e * 2 + 1] = sn; }
.Lmy_mdp_done:
.LBB0_378:
	v_lshl_add_u32 v6, s30, 9, v1
	s_mov_b32 s2, 0x10000
	v_cmp_gt_i32_e32 vcc, s2, v6
	s_and_saveexec_b64 s[10:11], vcc
	s_cbranch_execz .LBB0_385
	v_and_b32_e32 v2, 15, v1
	v_cvt_f32_ubyte0_e32 v2, v2
	v_mul_f32_e32 v7, 0xbd800000, v2
	v_mov_b32_e32 v2, 0x461c4000
	v_cmp_eq_f32_e32 vcc, 0, v7
	s_mov_b32 s2, 0x3f2aaaab
	s_movk_i32 s4, 0x204
	v_cndmask_b32_e64 v14, v2, 1.0, vcc
	v_frexp_mant_f32_e32 v2, v14
	v_cmp_gt_f32_e64 s[2:3], s2, v2
	s_mov_b32 s6, 0x42b17218
	s_mov_b32 s5, 0x7f800000
	v_cndmask_b32_e64 v3, 1.0, 2.0, s[2:3]
	v_mul_f32_e32 v2, v2, v3
	v_add_f32_e32 v5, 1.0, v2
	v_rcp_f32_e32 v12, v5
	v_add_f32_e32 v3, -1.0, v5
	v_sub_f32_e32 v9, v2, v3
	v_add_f32_e32 v3, -1.0, v2
	v_mul_f32_e32 v13, v3, v12
	v_mul_f32_e32 v4, v5, v13
	v_fma_f32 v8, v13, v5, -v4
	v_fmac_f32_e32 v8, v13, v9
	v_add_f32_e32 v2, v4, v8
	v_sub_f32_e32 v5, v3, v2
	v_pk_add_f32 v[10:11], v[2:3], v[4:5] neg_lo:[0,1] neg_hi:[0,1]
	v_mov_b32_e32 v9, v2
	v_pk_add_f32 v[2:3], v[10:11], v[8:9] neg_lo:[0,1] neg_hi:[0,1]
	v_mov_b32_e32 v8, 0x3e91f4c4
	v_add_f32_e32 v2, v2, v3
	v_add_f32_e32 v2, v5, v2
	v_mul_f32_e32 v3, v12, v2
	v_add_f32_e32 v2, v13, v3
	v_sub_f32_e32 v4, v2, v13
	v_sub_f32_e32 v15, v3, v4
	v_mul_f32_e32 v3, v2, v2
	v_fma_f32 v5, v2, v2, -v3
	v_add_f32_e32 v4, v15, v15
	v_fmac_f32_e32 v5, v2, v4
	v_add_f32_e32 v4, v3, v5
	v_fmac_f32_e32 v8, 0x3e76c4e1, v4
	v_fmaak_f32 v8, v4, v8, 0x3ecccdef
	v_sub_f32_e32 v3, v4, v3
	v_sub_f32_e32 v16, v5, v3
	v_mul_f32_e32 v3, v4, v8
	v_fma_f32 v5, v4, v8, -v3
	v_fmac_f32_e32 v5, v16, v8
	v_add_f32_e32 v8, v3, v5
	v_add_f32_e32 v9, 0x3f2aaaaa, v8
	v_sub_f32_e32 v3, v8, v3
	v_sub_f32_e32 v3, v5, v3
	v_add_f32_e32 v5, 0xbf2aaaaa, v9
	v_add_f32_e32 v3, 0x31739010, v3
	v_sub_f32_e32 v5, v8, v5
	v_pk_mul_f32 v[10:11], v[2:3], v[4:5]
	v_pk_add_f32 v[12:13], v[2:3], v[4:5]
	v_fma_f32 v8, v4, v2, -v10
	v_fmac_f32_e32 v8, v4, v15
	v_mov_b32_e32 v11, v13
	v_fmac_f32_e32 v8, v16, v2
	v_pk_add_f32 v[4:5], v[10:11], v[8:9]
	v_ldexp_f32 v16, v15, 1
	v_sub_f32_e32 v3, v4, v10
	v_sub_f32_e32 v3, v8, v3
	v_sub_f32_e32 v8, v9, v5
	v_add_f32_e32 v11, v13, v8
	v_pk_mul_f32 v[8:9], v[4:5], v[4:5] op_sel:[0,1] op_sel_hi:[1,0]
	v_cvt_f64_f32_e32 v[12:13], v14
	v_frexp_exp_i32_f64_e32 v9, v[12:13]
	v_subbrev_co_u32_e64 v9, s[2:3], 0, v9, s[2:3]
	v_cvt_f32_i32_e32 v9, v9
	v_fma_f32 v10, v4, v5, -v8
	v_fmac_f32_e32 v10, v4, v11
	s_mov_b32 s2, 0x3f317218
	v_mul_f32_e32 v4, 0x3f317218, v9
	v_fmac_f32_e32 v10, v3, v5
	v_fma_f32 v3, v9, s2, -v4
	v_fmamk_f32 v12, v9, 0xb102e308, v3
	v_ldexp_f32 v13, v2, 1
	v_add_f32_e32 v5, v8, v10
	v_pk_add_f32 v[2:3], v[4:5], v[12:13]
	v_mov_b32_e32 v14, v5
	v_mov_b32_e32 v15, v3
	v_mov_b32_e32 v9, v13
	v_pk_add_f32 v[8:9], v[14:15], v[8:9] neg_lo:[0,1] neg_hi:[0,1]
	v_mov_b32_e32 v11, v5
	v_pk_add_f32 v[8:9], v[10:11], v[8:9] neg_lo:[0,1] neg_hi:[0,1]
	v_mov_b32_e32 v13, v2
	v_add_f32_e32 v5, v16, v8
	v_add_f32_e32 v5, v5, v9
	v_pk_add_f32 v[8:9], v[2:3], v[4:5] neg_lo:[0,1] neg_hi:[0,1]
	v_pk_add_f32 v[10:11], v[2:3], v[4:5]
	v_mov_b32_e32 v4, v5
	v_mov_b32_e32 v9, v11
	v_pk_add_f32 v[14:15], v[12:13], v[8:9] neg_lo:[0,1] neg_hi:[0,1]
	v_pk_add_f32 v[8:9], v[12:13], v[8:9]
	v_mov_b32_e32 v5, v2
	v_pk_add_f32 v[12:13], v[8:9], v[2:3] op_sel:[1,0] op_sel_hi:[0,1] neg_lo:[0,1] neg_hi:[0,1]
	v_pk_add_f32 v[16:17], v[10:11], v[12:13] op_sel_hi:[1,0] neg_lo:[0,1] neg_hi:[0,1]
	v_mov_b32_e32 v10, v11
	v_mov_b32_e32 v11, v9
	v_pk_mov_b32 v[12:13], v[2:3], v[12:13] op_sel:[1,0]
	v_mov_b32_e32 v16, v14
	v_pk_add_f32 v[10:11], v[10:11], v[12:13] neg_lo:[0,1] neg_hi:[0,1]
	v_mov_b32_e32 v15, v9
	v_pk_add_f32 v[2:3], v[4:5], v[10:11] neg_lo:[0,1] neg_hi:[0,1]
	s_add_u32 s12, s16, 0x200000
	v_pk_add_f32 v[4:5], v[16:17], v[2:3]
	v_lshlrev_b32_e32 v1, 1, v1
	v_pk_add_f32 v[10:11], v[4:5], v[4:5] op_sel:[0,1] op_sel_hi:[1,0]
	s_addc_u32 s13, s17, 0
	v_pk_add_f32 v[8:9], v[8:9], v[10:11] op_sel:[1,0] op_sel_hi:[0,1]
	v_mov_b32_e32 v5, v8
	v_pk_add_f32 v[12:13], v[4:5], v[14:15] neg_lo:[0,1] neg_hi:[0,1]
	v_mov_b32_e32 v3, v10
	v_sub_f32_e32 v4, v4, v12
	v_pk_add_f32 v[2:3], v[2:3], v[12:13] neg_lo:[0,1] neg_hi:[0,1]
	v_sub_f32_e32 v4, v14, v4
	v_add_f32_e32 v2, v2, v4
	v_add_f32_e32 v2, v2, v3
	v_add_f32_e32 v3, v8, v2
	v_sub_f32_e32 v4, v3, v8
	v_sub_f32_e32 v2, v2, v4
	v_mul_f32_e32 v4, v7, v3
	v_fma_f32 v3, v7, v3, -v4
	v_fmac_f32_e32 v3, v7, v2
	v_add_f32_e32 v2, v4, v3
	v_cmp_class_f32_e64 s[2:3], v4, s4
	v_sub_f32_e32 v5, v2, v4
	v_sub_f32_e32 v3, v3, v5
	v_cndmask_b32_e64 v2, v2, v4, s[2:3]
	v_mov_b32_e32 v4, 0x37000000
	v_cmp_eq_f32_e64 s[2:3], s6, v2
	s_lshl_b32 s18, s9, 9
	s_lshl_b32 s9, s9, 10
	v_cndmask_b32_e64 v4, 0, v4, s[2:3]
	v_sub_f32_e32 v5, v2, v4
	s_mov_b32 s2, 0x3fb8aa3b
	v_mul_f32_e32 v8, 0x3fb8aa3b, v5
	v_fma_f32 v9, v5, s2, -v8
	v_rndne_f32_e32 v10, v8
	v_fmamk_f32 v9, v5, 0x32a5705f, v9
	v_sub_f32_e32 v8, v8, v10
	v_add_f32_e32 v8, v8, v9
	v_exp_f32_e32 v8, v8
	v_cvt_i32_f32_e32 v9, v10
	v_cmp_neq_f32_e64 s[2:3], |v2|, s5
	s_mov_b64 s[14:15], 0
	s_brev_b32 s19, 18
	v_cndmask_b32_e64 v2, 0, v3, s[2:3]
	s_mov_b32 s2, 0xc2ce8ed0
	v_ldexp_f32 v3, v8, v9
	v_cmp_ngt_f32_e64 s[2:3], s2, v5
	v_add_f32_e32 v2, v4, v2
	v_mov_b32_e32 v4, 0x7f800000
	v_cndmask_b32_e64 v3, 0, v3, s[2:3]
	v_cmp_nlt_f32_e64 s[2:3], s6, v5
	s_mov_b32 s20, 0xfe5163ab
	v_mov_b32_e32 v5, 0
	v_cndmask_b32_e64 v3, v4, v3, s[2:3]
	v_fma_f32 v2, v3, v2, v3
	v_cmp_class_f32_e64 s[2:3], v3, s4
	s_mov_b32 s21, 0x3c439041
	s_mov_b32 s22, 0xdb629599
	v_cndmask_b32_e64 v2, v2, v3, s[2:3]
	v_cmp_neq_f32_e64 s[2:3], v7, |v7|
	s_mov_b32 s23, 0xf534ddc0
	s_mov_b32 s24, 0xfc2757d1
	v_cndmask_b32_e64 v3, v4, 0, s[2:3]
	v_cndmask_b32_e64 v3, v3, 1.0, vcc
	v_cmp_class_f32_e64 s[2:3], v7, s4
	s_mov_b32 s25, 0x4e441529
	s_mov_b32 s26, 0xa2f9836e
	v_cndmask_b32_e64 v7, |v2|, v3, s[2:3]
	v_lshl_add_u32 v2, s30, 10, v1
	s_mov_b32 s27, 0x3fc90fda
	s_mov_b32 s28, 0x3f22f983
	s_mov_b32 s29, 0xbfc90fda
	v_mov_b32_e32 v1, 0x3c0881c4
	v_mov_b32_e32 v8, 0xbab64f3b
	s_brev_b32 s30, 1
	s_movk_i32 s31, 0x1f8
	s_mov_b32 s33, 0xffff
	v_not_b32_e32 v9, 63
	v_not_b32_e32 v10, 31
	v_mov_b32_e32 v11, 0x7fc00000
	s_branch .LBB0_381

; #define LAS __attribute__((address_space(3)))
; __device__ __forceinline__ float sigmoidf_(float x) { return 1.f / (1.f + __expf(-x)); }
; __device__ __forceinline__ void mod_items(ArgsP a, LAS unsigned char* lds, int bid, int G, int wave, int lane) {
;     LAS float* sil = (LAS float*)lds;
;     LAS float* part = (LAS float*)(lds + 40960);
;     float* MOD = (float*)(a->ws + WS_MOD); const int tid = wave * 64 + lane;
;     for (int e = tid; e < 5 * DM; e += 512) { const int b5 = e >> 11, k = e & 2047; const float cvv = b5 < 4 ? a->in[1][b5 * DM + k] : a->in[3][k]; sil[e] = cvv * sigmoidf_(cvv); }
;     __syncthreads();
;     for (int it = bid; it < 2 * 48; it += G) {
;         const int l = it / 48, cgp = it % 48, n0 = cgp * 256 + lane * 4, k0 = wave * 256;
;         const float* W = a->in[4] + (size_t)l * DM * 12288 + (size_t)k0 * 12288 + n0;
;         f32x4 acc[5];
; #pragma unroll
;         for (int b = 0; b < 5; ++b) acc[b] = (f32x4){0.f, 0.f, 0.f, 0.f};
.Lmy_cvm_done:
	s_and_b64 vcc, exec, s[66:67]
	s_cbranch_vccz .Lmy_mdw_done
	s_cmp_lt_u32 s8, 32
	s_cbranch_scc1 .Lmy_mdw_done
	s_waitcnt lgkmcnt(0)
	s_barrier
	v_and_b32_e32 v23, 63, v206
	v_lshrrev_b32_e32 v24, 6, v206
	s_load_dwordx2 s[14:15], s[0:1], 0x20
	s_load_dwordx2 s[18:19], s[0:1], 0x28
	s_load_dwordx2 s[20:21], s[0:1], 0xd0
	s_load_dwordx2 s[22:23], s[0:1], 0x8
	s_load_dwordx2 s[24:25], s[0:1], 0x18
	v_readfirstlane_b32 s2, v24
	v_lshlrev_b32_e32 v25, 4, v23
	s_waitcnt lgkmcnt(0)
	v_lshlrev_b32_e32 v26, 2, v206
	global_load_dword v27, v26, s[22:23]
	s_add_u32 s26, s22, 0x800
	s_addc_u32 s27, s23, 0
	global_load_dword v28, v26, s[26:27]
	s_add_u32 s26, s22, 0x1000
	s_addc_u32 s27, s23, 0
	global_load_dword v29, v26, s[26:27]
	s_add_u32 s26, s22, 0x1800
	s_addc_u32 s27, s23, 0
	global_load_dword v30, v26, s[26:27]
	s_add_u32 s26, s22, 0x2000
	s_addc_u32 s27, s23, 0
	global_load_dword v31, v26, s[26:27]
	s_add_u32 s26, s22, 0x2800
	s_addc_u32 s27, s23, 0
	global_load_dword v32, v26, s[26:27]
	s_add_u32 s26, s22, 0x3000
	s_addc_u32 s27, s23, 0
	global_load_dword v33, v26, s[26:27]
	s_add_u32 s26, s22, 0x3800
	s_addc_u32 s27, s23, 0
	global_load_dword v34, v26, s[26:27]
	s_add_u32 s26, s22, 0x4000
	s_addc_u32 s27, s23, 0
	global_load_dword v35, v26, s[26:27]
	s_add_u32 s26, s22, 0x4800
	s_addc_u32 s27, s23, 0
	global_load_dword v36, v26, s[26:27]
	s_add_u32 s26, s22, 0x5000
	s_addc_u32 s27, s23, 0
	global_load_dword v37, v26, s[26:27]
	s_add_u32 s26, s22, 0x5800
	s_addc_u32 s27, s23, 0
	global_load_dword v38, v26, s[26:27]
	s_add_u32 s26, s22, 0x6000
	s_addc_u32 s27, s23, 0
	global_load_dword v39, v26, s[26:27]
	s_add_u32 s26, s22, 0x6800
	s_addc_u32 s27, s23, 0
	global_load_dword v40, v26, s[26:27]
	s_add_u32 s26, s22, 0x7000
	s_addc_u32 s27, s23, 0
	global_load_dword v41, v26, s[26:27]
	s_add_u32 s26, s22, 0x7800
	s_addc_u32 s27, s23, 0
	global_load_dword v42, v26, s[26:27]
	global_load_dword v43, v26, s[24:25]
	s_add_u32 s26, s24, 0x800
	s_addc_u32 s27, s25, 0
	global_load_dword v44, v26, s[26:27]
	s_add_u32 s26, s24, 0x1000
	s_addc_u32 s27, s25, 0
	global_load_dword v45, v26, s[26:27]
	s_add_u32 s26, s24, 0x1800
	s_addc_u32 s27, s25, 0
	global_load_dword v46, v26, s[26:27]
	s_waitcnt vmcnt(19)
	v_mul_f32_e32 v164, 0xbfb8aa3b, v27
	s_waitcnt vmcnt(18)
	v_mul_f32_e32 v165, 0xbfb8aa3b, v28
	s_waitcnt vmcnt(17)
	v_mul_f32_e32 v166, 0xbfb8aa3b, v29
	s_waitcnt vmcnt(16)
	v_mul_f32_e32 v167, 0xbfb8aa3b, v30
	s_waitcnt vmcnt(15)
	v_mul_f32_e32 v168, 0xbfb8aa3b, v31
	s_waitcnt vmcnt(14)
	v_mul_f32_e32 v169, 0xbfb8aa3b, v32
	s_waitcnt vmcnt(13)
	v_mul_f32_e32 v170, 0xbfb8aa3b, v33
	s_waitcnt vmcnt(12)
	v_mul_f32_e32 v171, 0xbfb8aa3b, v34
	s_waitcnt vmcnt(11)
	v_mul_f32_e32 v172, 0xbfb8aa3b, v35
	s_waitcnt vmcnt(10)
	v_mul_f32_e32 v173, 0xbfb8aa3b, v36
	s_waitcnt vmcnt(9)
	v_mul_f32_e32 v174, 0xbfb8aa3b, v37
	s_waitcnt vmcnt(8)
	v_mul_f32_e32 v175, 0xbfb8aa3b, v38
	s_waitcnt vmcnt(7)
	v_mul_f32_e32 v176, 0xbfb8aa3b, v39
	s_waitcnt vmcnt(6)
	v_mul_f32_e32 v177, 0xbfb8aa3b, v40
	s_waitcnt vmcnt(5)
	v_mul_f32_e32 v178, 0xbfb8aa3b, v41
	s_waitcnt vmcnt(4)
	v_mul_f32_e32 v179, 0xbfb8aa3b, v42
	s_waitcnt vmcnt(3)
	v_mul_f32_e32 v180, 0xbfb8aa3b, v43
	s_waitcnt vmcnt(2)
	v_mul_f32_e32 v181, 0xbfb8aa3b, v44
	s_waitcnt vmcnt(1)
	v_mul_f32_e32 v182, 0xbfb8aa3b, v45
	s_waitcnt vmcnt(0)
	v_mul_f32_e32 v183, 0xbfb8aa3b, v46
	v_exp_f32_e32 v164, v164
	v_exp_f32_e32 v165, v165
	v_exp_f32_e32 v166, v166
	v_exp_f32_e32 v167, v167
	v_exp_f32_e32 v168, v168
	v_exp_f32_e32 v169, v169
	v_exp_f32_e32 v170, v170
	v_exp_f32_e32 v171, v171
	v_exp_f32_e32 v172, v172
	v_exp_f32_e32 v173, v173
	v_exp_f32_e32 v174, v174
	v_exp_f32_e32 v175, v175
	v_exp_f32_e32 v176, v176
	v_exp_f32_e32 v177, v177
	v_exp_f32_e32 v178, v178
	v_exp_f32_e32 v179, v179
	v_exp_f32_e32 v180, v180
	v_exp_f32_e32 v181, v181
	v_exp_f32_e32 v182, v182
	v_exp_f32_e32 v183, v183
	v_add_f32_e32 v164, 1.0, v164
	v_add_f32_e32 v165, 1.0, v165
	v_add_f32_e32 v166, 1.0, v166
	v_add_f32_e32 v167, 1.0, v167
	v_add_f32_e32 v168, 1.0, v168
	v_add_f32_e32 v169, 1.0, v169
	v_add_f32_e32 v170, 1.0, v170
	v_add_f32_e32 v171, 1.0, v171
	v_add_f32_e32 v172, 1.0, v172
	v_add_f32_e32 v173, 1.0, v173
	v_add_f32_e32 v174, 1.0, v174
	v_add_f32_e32 v175, 1.0, v175
	v_add_f32_e32 v176, 1.0, v176
	v_add_f32_e32 v177, 1.0, v177
	v_add_f32_e32 v178, 1.0, v178
	v_add_f32_e32 v179, 1.0, v179
	v_add_f32_e32 v180, 1.0, v180
	v_add_f32_e32 v181, 1.0, v181
	v_add_f32_e32 v182, 1.0, v182
	v_add_f32_e32 v183, 1.0, v183
	v_rcp_f32_e32 v164, v164
	v_rcp_f32_e32 v165, v165
	v_rcp_f32_e32 v166, v166
	v_rcp_f32_e32 v167, v167
	v_rcp_f32_e32 v168, v168
	v_rcp_f32_e32 v169, v169
	v_rcp_f32_e32 v170, v170
	v_rcp_f32_e32 v171, v171
	v_rcp_f32_e32 v172, v172
	v_rcp_f32_e32 v173, v173
	v_rcp_f32_e32 v174, v174
	v_rcp_f32_e32 v175, v175
	v_rcp_f32_e32 v176, v176
	v_rcp_f32_e32 v177, v177
	v_rcp_f32_e32 v178, v178
	v_rcp_f32_e32 v179, v179
	v_rcp_f32_e32 v180, v180
	v_rcp_f32_e32 v181, v181
	v_rcp_f32_e32 v182, v182
	v_rcp_f32_e32 v183, v183
	v_mul_f32_e32 v27, v27, v164
	v_mul_f32_e32 v28, v28, v165
	v_mul_f32_e32 v29, v29, v166
	v_mul_f32_e32 v30, v30, v167
	v_mul_f32_e32 v31, v31, v168
	v_mul_f32_e32 v32, v32, v169
	v_mul_f32_e32 v33, v33, v170
	v_mul_f32_e32 v34, v34, v171
	v_mul_f32_e32 v35, v35, v172
	v_mul_f32_e32 v36, v36, v173
	v_mul_f32_e32 v37, v37, v174
	v_mul_f32_e32 v38, v38, v175
	v_mul_f32_e32 v39, v39, v176
	v_mul_f32_e32 v40, v40, v177
	v_mul_f32_e32 v41, v41, v178
	v_mul_f32_e32 v42, v42, v179
	v_mul_f32_e32 v43, v43, v180
	v_mul_f32_e32 v44, v44, v181
	v_mul_f32_e32 v45, v45, v182
	v_mul_f32_e32 v46, v46, v183
	ds_write_b32 v26, v27
	ds_write_b32 v26, v28 offset:2048
	ds_write_b32 v26, v29 offset:4096
	ds_write_b32 v26, v30 offset:6144
	ds_write_b32 v26, v31 offset:8192
	ds_write_b32 v26, v32 offset:10240
	ds_write_b32 v26, v33 offset:12288
	ds_write_b32 v26, v34 offset:14336
	ds_write_b32 v26, v35 offset:16384
	ds_write_b32 v26, v36 offset:18432
	ds_write_b32 v26, v37 offset:20480
	ds_write_b32 v26, v38 offset:22528
	ds_write_b32 v26, v39 offset:24576
	ds_write_b32 v26, v40 offset:26624
	ds_write_b32 v26, v41 offset:28672
	ds_write_b32 v26, v42 offset:30720
	ds_write_b32 v26, v43 offset:32768
	ds_write_b32 v26, v44 offset:34816
	ds_write_b32 v26, v45 offset:36864
	ds_write_b32 v26, v46 offset:38912
	s_waitcnt lgkmcnt(0)
	s_barrier
	s_lshl_b32 s4, s2, 4
	s_mul_i32 s5, s2, 0x1400
	v_add_u32_e32 v27, s5, v25
	v_add_u32_e32 v27, 0xa000, v27
	v_lshlrev_b32_e32 v28, 2, v206
	v_add_u32_e32 v28, 0xa000, v28
	v_lshrrev_b32_e32 v29, 8, v206
	v_and_b32_e32 v30, 0xff, v206
	v_mul_u32_u24_e32 v29, 0x3000, v29
	v_add_u32_e32 v29, v29, v30
	v_lshlrev_b32_e32 v29, 2, v29
	v_lshlrev_b32_e32 v30, 2, v30
	s_add_u32 s20, s20, 0x100000
	s_addc_u32 s21, s21, 0
	s_sub_i32 s3, s8, 32
	s_add_i32 s3, s3, 256
	s_cmp_ge_u32 s3, 1536
	s_cbranch_scc1 .Lmy_mdw_done

; __device__ __forceinline__ void mod_items(ArgsP a, LAS unsigned char* lds, int bid, int G, int wave, int lane) {
;     ...
;         __syncthreads();
;         for (int e = tid; e < 5 * 256; e += 512) { const int b = e >> 8, cidx = e & 255; float sacc = a->in[5][l * 12288 + cgp * 256 + cidx];
; #pragma unroll
;             for (int w8 = 0; w8 < 8; ++w8) sacc += part[(w8 * 5 + b) * 256 + cidx];
;             MOD[(size_t)(l * 5 + b) * 12288 + cgp * 256 + cidx] = sacc; }
;         __syncthreads();
;     }
.Lmy_mdw_nb2:
	s_waitcnt lgkmcnt(0)
	v_add_f32_e32 v64, v64, v65
	v_add_f32_e32 v66, v66, v67
	v_add_f32_e32 v68, v68, v70
	v_add_f32_e32 v71, v71, v72
	v_add_f32_e32 v64, v64, v66
	v_add_f32_e32 v68, v68, v71
	v_add_f32_e32 v64, v64, v68
	s_waitcnt vmcnt(0)
	v_add_f32_e32 v64, v64, v73
	s_add_u32 s68, s68, 0x18000
	s_addc_u32 s69, s69, 0
	global_atomic_add_f32 v29, v64, s[68:69]
	s_or_b64 exec, exec, s[58:59]
	s_barrier
	s_add_i32 s3, s3, 224
	s_cmp_lt_u32 s3, 1536
	s_cbranch_scc1 .Lmy_mdw_loop
